# v23
# speedup vs baseline: 1.0083x; 1.0032x over previous
.LBB0_193:
	ds_read_b128 v[64:67], v180 offset:49152
	ds_read_b128 v[68:71], v180 offset:57344
	ds_read_b128 v[128:131], v179 offset:49152
	s_waitcnt vmcnt(2)
	ds_read_b128 v[132:135], v179 offset:57344
	ds_read_b128 v[248:251], v165 offset:49152
	ds_read_b128 v[252:255], v165 offset:57344
	s_waitcnt vmcnt(1)
	v_exp_f32_e32 v136, v144
	v_add_f32_e32 v144, 0, v216
	s_waitcnt lgkmcnt(5)
	v_mfma_f32_32x32x16_bf16 v[80:95], v[64:67], v[124:127], 0
	v_add_f32_e32 v144, v219, v144
	v_add_f32_e32 v144, v213, v144
	v_add_f32_e32 v144, v217, v144
	v_add_f32_e32 v144, v212, v144
	v_add_f32_e32 v144, v214, v144
	v_add_f32_e32 v144, v210, v144
	v_add_f32_e32 v144, v211, v144
	s_waitcnt lgkmcnt(4)
	v_mfma_f32_32x32x16_bf16 v[64:79], v[68:71], v[124:127], 0
	v_add_f32_e32 v144, v207, v144
	v_add_f32_e32 v144, v209, v144
	v_add_f32_e32 v144, v206, v144
	v_add_f32_e32 v144, v208, v144
	v_add_f32_e32 v144, v195, v144
	v_add_f32_e32 v144, v197, v144
	v_add_f32_e32 v144, v194, v144
	s_waitcnt lgkmcnt(3)
	v_mfma_f32_32x32x16_bf16 v[80:95], v[128:131], v[120:123], v[80:95]
	v_add_f32_e32 v144, v196, v144
	v_exp_f32_e32 v137, v145
	v_exp_f32_e32 v138, v158
	v_exp_f32_e32 v139, v159
	s_waitcnt vmcnt(0)
	v_exp_f32_e32 v140, v152
	v_exp_f32_e32 v141, v153
	v_exp_f32_e32 v142, v146
	s_waitcnt lgkmcnt(2)
	v_mfma_f32_32x32x16_bf16 v[64:79], v[132:135], v[120:123], v[64:79]
	ds_read_b128 v[128:131], v163 offset:49152
	ds_read_b128 v[132:135], v163 offset:57344
	v_exp_f32_e32 v143, v147
	s_sub_i32 s0, s26, 63
	s_waitcnt lgkmcnt(3)
	v_mfma_f32_32x32x16_bf16 v[80:95], v[248:251], v[116:119], v[80:95]
	s_waitcnt lgkmcnt(2)
	v_mfma_f32_32x32x16_bf16 v[64:79], v[252:255], v[116:119], v[64:79]
	ds_read_b128 v[248:251], v180 offset:49280
	ds_read_b128 v[252:255], v180 offset:57472
	s_waitcnt lgkmcnt(3)
	v_mfma_f32_32x32x16_bf16 v[80:95], v[128:131], v[112:115], v[80:95]
	s_waitcnt lgkmcnt(2)
	v_mfma_f32_32x32x16_bf16 v[64:79], v[132:135], v[112:115], v[64:79]
	ds_read_b128 v[128:131], v179 offset:49280
	ds_read_b128 v[132:135], v179 offset:57472
	s_waitcnt lgkmcnt(3)
	v_mfma_f32_32x32x16_bf16 v[80:95], v[248:251], v[108:111], v[80:95]
	s_waitcnt lgkmcnt(2)
	v_mfma_f32_32x32x16_bf16 v[64:79], v[252:255], v[108:111], v[64:79]
	ds_read_b128 v[248:251], v165 offset:49280
	ds_read_b128 v[252:255], v165 offset:57472
	s_waitcnt lgkmcnt(3)
	v_mfma_f32_32x32x16_bf16 v[80:95], v[128:131], v[104:107], v[80:95]
	s_waitcnt lgkmcnt(2)
	v_mfma_f32_32x32x16_bf16 v[64:79], v[132:135], v[104:107], v[64:79]
	ds_read_b128 v[128:131], v163 offset:49280
	ds_read_b128 v[132:135], v163 offset:57472
	s_waitcnt lgkmcnt(3)
	v_mfma_f32_32x32x16_bf16 v[80:95], v[248:251], v[100:103], v[80:95]
	s_waitcnt lgkmcnt(2)
	v_mfma_f32_32x32x16_bf16 v[64:79], v[252:255], v[100:103], v[64:79]
	s_waitcnt lgkmcnt(1)
	v_mfma_f32_32x32x16_bf16 v[80:95], v[128:131], v[96:99], v[80:95]
	v_exp_f32_e32 v128, v156
	v_exp_f32_e32 v129, v157
	v_exp_f32_e32 v130, v154
	v_exp_f32_e32 v131, v155
	v_add_f32_e32 v144, v128, v144
	v_add_f32_e32 v144, v129, v144
	v_add_f32_e32 v144, v130, v144
	s_waitcnt lgkmcnt(0)
	v_mfma_f32_32x32x16_bf16 v[64:79], v[132:135], v[96:99], v[64:79]
	v_exp_f32_e32 v132, v150
	v_exp_f32_e32 v133, v151
	v_exp_f32_e32 v134, v148
	v_exp_f32_e32 v135, v149
	v_add_f32_e32 v144, v131, v144
	v_add_f32_e32 v144, v132, v144
	v_add_f32_e32 v144, v133, v144
	v_add_f32_e32 v144, v134, v144
	v_add_f32_e32 v144, v135, v144
	v_add_f32_e32 v144, v136, v144
	v_add_f32_e32 v144, v137, v144
	v_add_f32_e32 v144, v138, v144
	v_add_f32_e32 v144, v139, v144
	v_add_f32_e32 v144, v140, v144
	v_add_f32_e32 v144, v141, v144
	v_add_f32_e32 v144, v142, v144
	v_add_f32_e32 v190, v143, v144
	v_mov_b32_e32 v191, v190
	s_nop 1
	v_permlane32_swap_b32_e32 v190, v191
	s_nop 0
	v_cvt_pk_bf16_f32 v144, v216, v219
	s_nop 0
	v_cvt_pk_bf16_f32 v145, v213, v217
	s_nop 0
	v_cvt_pk_bf16_f32 v146, v212, v214
	s_nop 0
	v_cvt_pk_bf16_f32 v147, v210, v211
	s_nop 0
	v_cvt_pk_bf16_f32 v148, v207, v209
	s_nop 0
	v_cvt_pk_bf16_f32 v149, v206, v208
	s_nop 0
	v_cvt_pk_bf16_f32 v150, v195, v197
	s_nop 0
	v_cvt_pk_bf16_f32 v151, v194, v196
	s_nop 0
	v_cvt_pk_bf16_f32 v152, v128, v129
	s_nop 0
	v_cvt_pk_bf16_f32 v153, v130, v131
	s_nop 0
	v_cvt_pk_bf16_f32 v154, v132, v133
	s_nop 0
	v_cvt_pk_bf16_f32 v155, v134, v135
	s_nop 0
	v_cvt_pk_bf16_f32 v156, v136, v137
	s_nop 0
	v_cvt_pk_bf16_f32 v157, v138, v139
	s_nop 0
	v_cvt_pk_bf16_f32 v158, v140, v141
	s_nop 0
	v_cvt_pk_bf16_f32 v159, v142, v143
	s_nop 0
	v_permlane32_swap_b32_e32 v144, v146
	v_permlane32_swap_b32_e32 v145, v147
	v_permlane32_swap_b32_e32 v148, v150
	v_permlane32_swap_b32_e32 v149, v151
	v_permlane32_swap_b32_e32 v152, v154
	v_permlane32_swap_b32_e32 v153, v155
	v_permlane32_swap_b32_e32 v156, v158
	v_permlane32_swap_b32_e32 v157, v159
	v_add_u32_e32 v192, s26, v160
	v_add_u32_e32 v128, 1, v192
	v_add_u32_e32 v130, 33, v192
	v_ashrrev_i32_e32 v129, 31, v128
	v_ashrrev_i32_e32 v131, 31, v130
	v_lshlrev_b64 v[136:137], 8, v[128:129]
	v_lshlrev_b64 v[138:139], 8, v[130:131]
	v_lshl_add_u64 v[128:129], v[166:167], 0, v[136:137]
	v_lshl_add_u64 v[132:133], v[166:167], 0, v[138:139]
	v_lshl_add_u64 v[136:137], v[168:169], 0, v[136:137]
	v_lshl_add_u64 v[140:141], v[168:169], 0, v[138:139]
	global_load_dwordx4 v[128:131], v[128:129], off
	s_nop 0
	global_load_dwordx4 v[132:135], v[132:133], off
	s_nop 0
	global_load_dwordx4 v[136:139], v[136:137], off
	s_nop 0
	global_load_dwordx4 v[140:143], v[140:141], off
	ds_read_b64_tr_b16 v[194:195], v173 offset:0
	ds_read_b64_tr_b16 v[196:197], v173 offset:0x800
	ds_read_b64_tr_b16 v[206:207], v173 offset:0x1000
	ds_read_b64_tr_b16 v[208:209], v173 offset:0x1800
	ds_read_b64_tr_b16 v[210:211], v173 offset:0x2000
	ds_read_b64_tr_b16 v[212:213], v173 offset:0x2800
	ds_read_b64_tr_b16 v[214:215], v173 offset:0x3000
	ds_read_b64_tr_b16 v[216:217], v173 offset:0x3800
	s_waitcnt lgkmcnt(0)
	s_nop 0
	v_mfma_f32_32x32x16_bf16 v[48:63], v[144:147], v[194:197], v[48:63]
	ds_read_b64_tr_b16 v[194:195], v173 offset:0x200
	ds_read_b64_tr_b16 v[196:197], v173 offset:0xa00
	v_mfma_f32_32x32x16_bf16 v[48:63], v[148:151], v[206:209], v[48:63]
	ds_read_b64_tr_b16 v[206:207], v173 offset:0x1200
	ds_read_b64_tr_b16 v[208:209], v173 offset:0x1a00
	v_mfma_f32_32x32x16_bf16 v[48:63], v[152:155], v[210:213], v[48:63]
	ds_read_b64_tr_b16 v[210:211], v173 offset:0x2200
	ds_read_b64_tr_b16 v[212:213], v173 offset:0x2a00
	v_mfma_f32_32x32x16_bf16 v[48:63], v[156:159], v[214:217], v[48:63]
	ds_read_b64_tr_b16 v[214:215], v173 offset:0x3200
	ds_read_b64_tr_b16 v[216:217], v173 offset:0x3a00
	s_waitcnt lgkmcnt(0)
	v_mfma_f32_32x32x16_bf16 v[32:47], v[144:147], v[194:197], v[32:47]
	ds_read_b64_tr_b16 v[194:195], v173 offset:0x400
	ds_read_b64_tr_b16 v[196:197], v173 offset:0xc00
	v_mfma_f32_32x32x16_bf16 v[32:47], v[148:151], v[206:209], v[32:47]
	ds_read_b64_tr_b16 v[206:207], v173 offset:0x1400
	ds_read_b64_tr_b16 v[208:209], v173 offset:0x1c00
	v_mfma_f32_32x32x16_bf16 v[32:47], v[152:155], v[210:213], v[32:47]
	ds_read_b64_tr_b16 v[210:211], v173 offset:0x2400
	ds_read_b64_tr_b16 v[212:213], v173 offset:0x2c00
	v_mfma_f32_32x32x16_bf16 v[32:47], v[156:159], v[214:217], v[32:47]
	ds_read_b64_tr_b16 v[214:215], v173 offset:0x3400
	ds_read_b64_tr_b16 v[216:217], v173 offset:0x3c00
	s_waitcnt lgkmcnt(0)
	v_mfma_f32_32x32x16_bf16 v[16:31], v[144:147], v[194:197], v[16:31]
	ds_read_b64_tr_b16 v[194:195], v173 offset:0x600
	ds_read_b64_tr_b16 v[196:197], v173 offset:0xe00
	v_mfma_f32_32x32x16_bf16 v[16:31], v[148:151], v[206:209], v[16:31]
	ds_read_b64_tr_b16 v[206:207], v173 offset:0x1600
	ds_read_b64_tr_b16 v[208:209], v173 offset:0x1e00
	v_mfma_f32_32x32x16_bf16 v[16:31], v[152:155], v[210:213], v[16:31]
	ds_read_b64_tr_b16 v[210:211], v173 offset:0x2600
	ds_read_b64_tr_b16 v[212:213], v173 offset:0x2e00
	v_mfma_f32_32x32x16_bf16 v[16:31], v[156:159], v[214:217], v[16:31]
	ds_read_b64_tr_b16 v[214:215], v173 offset:0x3600
	ds_read_b64_tr_b16 v[216:217], v173 offset:0x3e00
	s_waitcnt lgkmcnt(0)
	v_mfma_f32_32x32x16_bf16 v[0:15], v[144:147], v[194:197], v[0:15]
	s_cmp_le_i32 s26, s19
	s_cselect_b64 s[2:3], -1, 0
	s_cmp_gt_i32 s0, s24
	s_cselect_b64 s[0:1], -1, 0
	s_and_b64 s[0:1], s[2:3], s[0:1]
	s_and_b64 vcc, exec, s[0:1]
	v_mfma_f32_32x32x16_bf16 v[0:15], v[148:151], v[206:209], v[0:15]
	v_mfma_f32_32x32x16_bf16 v[0:15], v[152:155], v[210:213], v[0:15]
	v_mfma_f32_32x32x16_bf16 v[0:15], v[156:159], v[214:217], v[0:15]
	s_waitcnt vmcnt(0)
	ds_write_b128 v176, v[136:139] offset:32768
	ds_write_b128 v176, v[140:143] offset:40960
	s_cbranch_vccnz .LBB0_195
	v_add_u32_e32 v144, 0x207b, v188
	v_cmp_gt_u32_e32 vcc, s73, v144
	v_add_u32_e32 v144, 0x5b, v188
	s_nop 0
	v_cndmask_b32_e32 v80, v202, v80, vcc
	v_cmp_lt_u32_e32 vcc, s95, v144
	v_add_u32_e32 v144, 0x7a, v188
	s_nop 0
	v_cndmask_b32_e32 v64, v202, v64, vcc
	v_cmp_lt_u32_e32 vcc, s95, v144
	v_add_u32_e32 v144, 0x5a, v188
	s_nop 0
	v_cndmask_b32_e32 v81, v202, v81, vcc
	v_cmp_lt_u32_e32 vcc, s95, v144
	v_add_u32_e32 v144, 0x79, v188
	s_nop 0
	v_cndmask_b32_e32 v65, v202, v65, vcc
	v_cmp_lt_u32_e32 vcc, s95, v144
	v_add_u32_e32 v144, 0x59, v188
	s_nop 0
	v_cndmask_b32_e32 v82, v202, v82, vcc
	v_cmp_lt_u32_e32 vcc, s95, v144
	v_add_u32_e32 v144, 0x78, v188
	s_nop 0
	v_cndmask_b32_e32 v66, v202, v66, vcc
	v_cmp_lt_u32_e32 vcc, s95, v144
	v_add_u32_e32 v144, 0x58, v188
	s_nop 0
	v_cndmask_b32_e32 v83, v202, v83, vcc
	v_cmp_lt_u32_e32 vcc, s95, v144
	v_add_u32_e32 v144, 0x73, v188
	s_nop 0
	v_cndmask_b32_e32 v67, v202, v67, vcc
	v_cmp_lt_u32_e32 vcc, s95, v144
	v_add_u32_e32 v144, 0x53, v188
	s_nop 0
	v_cndmask_b32_e32 v84, v202, v84, vcc
	v_cmp_lt_u32_e32 vcc, s95, v144
	v_add_u32_e32 v144, 0x72, v188
	s_nop 0
	v_cndmask_b32_e32 v68, v202, v68, vcc
	v_cmp_lt_u32_e32 vcc, s95, v144
	v_add_u32_e32 v144, 0x52, v188
	s_nop 0
	v_cndmask_b32_e32 v85, v202, v85, vcc
	v_cmp_lt_u32_e32 vcc, s95, v144
	v_add_u32_e32 v144, 0x71, v188
	s_nop 0
	v_cndmask_b32_e32 v69, v202, v69, vcc
	v_cmp_lt_u32_e32 vcc, s95, v144
	v_add_u32_e32 v144, 0x51, v188
	s_nop 0
	v_cndmask_b32_e32 v86, v202, v86, vcc
	v_cmp_lt_u32_e32 vcc, s95, v144
	v_add_u32_e32 v144, 0x70, v188
	s_nop 0
	v_cndmask_b32_e32 v70, v202, v70, vcc
	v_cmp_lt_u32_e32 vcc, s95, v144
	v_add_u32_e32 v144, 0x50, v188
	s_nop 0
	v_cndmask_b32_e32 v87, v202, v87, vcc
	v_cmp_lt_u32_e32 vcc, s95, v144
	v_add_u32_e32 v144, 0x6b, v188
	s_nop 0
	v_cndmask_b32_e32 v71, v202, v71, vcc
	v_cmp_lt_u32_e32 vcc, s95, v144
	v_add_u32_e32 v144, 0x4b, v188
	s_nop 0
	v_cndmask_b32_e32 v88, v202, v88, vcc
	v_cmp_lt_u32_e32 vcc, s95, v144
	v_add_u32_e32 v144, 0x6a, v188
	s_nop 0
	v_cndmask_b32_e32 v72, v202, v72, vcc
	v_cmp_lt_u32_e32 vcc, s95, v144
	v_add_u32_e32 v144, 0x4a, v188
	s_nop 0
	v_cndmask_b32_e32 v89, v202, v89, vcc
	v_cmp_lt_u32_e32 vcc, s95, v144
	v_add_u32_e32 v144, 0x69, v188
	s_nop 0
	v_cndmask_b32_e32 v73, v202, v73, vcc
	v_cmp_lt_u32_e32 vcc, s95, v144
	v_add_u32_e32 v144, 0x49, v188
	s_nop 0
	v_cndmask_b32_e32 v90, v202, v90, vcc
	v_cmp_lt_u32_e32 vcc, s95, v144
	v_add_u32_e32 v144, 0x68, v188
	s_nop 0
	v_cndmask_b32_e32 v74, v202, v74, vcc
	v_cmp_lt_u32_e32 vcc, s95, v144
	v_add_u32_e32 v144, 0x48, v188
	s_nop 0
	v_cndmask_b32_e32 v91, v202, v91, vcc
	v_cmp_lt_u32_e32 vcc, s95, v144
	v_add_u32_e32 v144, 0x63, v188
	s_nop 0
	v_cndmask_b32_e32 v75, v202, v75, vcc
	v_cmp_lt_u32_e32 vcc, s95, v144
	v_add_u32_e32 v144, 0x43, v188
	s_nop 0
	v_cndmask_b32_e32 v92, v202, v92, vcc
	v_cmp_lt_u32_e32 vcc, s95, v144
	v_add_u32_e32 v144, 0x62, v188
	s_nop 0
	v_cndmask_b32_e32 v76, v202, v76, vcc
	v_cmp_lt_u32_e32 vcc, s95, v144
	v_add_u32_e32 v144, 0x42, v188
	s_nop 0
	v_cndmask_b32_e32 v93, v202, v93, vcc
	v_cmp_lt_u32_e32 vcc, s95, v144
	v_add_u32_e32 v144, 0x61, v188
	s_nop 0
	v_cndmask_b32_e32 v77, v202, v77, vcc
	v_cmp_lt_u32_e32 vcc, s95, v144
	v_add_u32_e32 v144, 0x41, v188
	s_nop 0
	v_cndmask_b32_e32 v94, v202, v94, vcc
	v_cmp_lt_u32_e32 vcc, s95, v144
	v_add_u32_e32 v144, 0x60, v188
	s_nop 0
	v_cndmask_b32_e32 v78, v202, v78, vcc
	v_cmp_lt_u32_e32 vcc, s95, v144
	v_add_u32_e32 v144, 64, v188
	s_nop 0
	v_cndmask_b32_e32 v95, v202, v95, vcc
	v_cmp_lt_u32_e32 vcc, s95, v144
	s_nop 1
	v_cndmask_b32_e32 v79, v202, v79, vcc
.LBB0_195:
	v_max_f32_e32 v144, v81, v81
	v_max_f32_e32 v145, v80, v80
	v_max_f32_e32 v144, v145, v144
	v_max3_f32 v144, v144, v82, v83
	v_max3_f32 v144, v144, v84, v85
	v_max3_f32 v144, v144, v86, v87
	v_max3_f32 v144, v144, v88, v89
	v_max3_f32 v144, v144, v90, v91
	v_max3_f32 v144, v144, v92, v93
	v_max3_f32 v144, v144, v94, v95
	v_max3_f32 v144, v144, v64, v65
	v_max3_f32 v144, v144, v66, v67
	v_max3_f32 v144, v144, v68, v69
	v_max3_f32 v144, v144, v70, v71
	v_max3_f32 v144, v144, v72, v73
	v_max3_f32 v144, v144, v74, v75
	v_max3_f32 v144, v144, v76, v77
	v_max3_f32 v144, v144, v78, v79
	v_mov_b32_e32 v145, v144
	s_nop 1
	v_permlane32_swap_b32_e32 v144, v145
	v_max_f32_e32 v145, v145, v145
	v_max_f32_e32 v144, v144, v144
	v_max_f32_e32 v144, v144, v145
	v_sub_f32_e32 v145, v144, v186
	v_mul_f32_e32 v145, 0x3db504f3, v145
	v_cmp_ge_f32_e32 vcc, s87, v145
	v_max_f32_e32 v145, v186, v186
	v_max_f32_e32 v144, v145, v144
	v_sub_f32_e32 v145, v186, v144
	v_mul_f32_e32 v145, 0x3e0293ee, v145
	v_exp_f32_e32 v145, v145
	s_cmp_eq_u64 vcc, exec
	s_cselect_b64 s[0:1], -1, 0
	v_readfirstlane_b32 s27, v187
	s_nop 3
	s_cmpk_lt_u32 s27, 0x100
	s_cbranch_scc1 .Lg1b_hs1
	s_waitcnt lgkmcnt(0)
	s_barrier
	s_waitcnt vmcnt(0)
	v_cndmask_b32_e64 v193, v145, 1.0, s[0:1]
	v_cmp_gt_f32_e32 vcc, 1.0, v193
	s_waitcnt vmcnt(3)
	ds_write_b128 v181, v[128:131]
	s_waitcnt vmcnt(2)
	ds_write_b128 v182, v[132:135]
	s_cbranch_vccz .LBB0_199
	s_and_saveexec_b64 s[2:3], s[4:5]
	ds_write_b32 v175, v193 offset:128
	s_or_b64 exec, exec, s[2:3]
	s_waitcnt lgkmcnt(0)
	ds_read_b128 v[146:149], v174 offset:224
	ds_read_b128 v[150:153], v174 offset:192
	ds_read_b128 v[154:157], v174 offset:160
	ds_read_b128 v[194:197], v174 offset:128
	s_waitcnt lgkmcnt(3)
	v_pk_mul_f32 v[62:63], v[62:63], v[148:149]
	s_waitcnt lgkmcnt(2)
	v_pk_mul_f32 v[58:59], v[58:59], v[152:153]
	s_waitcnt lgkmcnt(1)
	v_pk_mul_f32 v[54:55], v[54:55], v[156:157]
	s_waitcnt lgkmcnt(0)
	v_pk_mul_f32 v[50:51], v[50:51], v[196:197]
	v_pk_mul_f32 v[60:61], v[60:61], v[146:147]
	v_pk_mul_f32 v[56:57], v[56:57], v[150:151]
	v_pk_mul_f32 v[52:53], v[52:53], v[154:155]
	v_pk_mul_f32 v[48:49], v[48:49], v[194:195]
	v_pk_mul_f32 v[46:47], v[46:47], v[148:149]
	v_pk_mul_f32 v[42:43], v[42:43], v[152:153]
	v_pk_mul_f32 v[38:39], v[38:39], v[156:157]
	v_pk_mul_f32 v[34:35], v[34:35], v[196:197]
	v_pk_mul_f32 v[44:45], v[44:45], v[146:147]
	v_pk_mul_f32 v[40:41], v[40:41], v[150:151]
	v_pk_mul_f32 v[36:37], v[36:37], v[154:155]
	v_pk_mul_f32 v[32:33], v[32:33], v[194:195]
	v_pk_mul_f32 v[30:31], v[30:31], v[148:149]
	v_pk_mul_f32 v[26:27], v[26:27], v[152:153]
	v_pk_mul_f32 v[22:23], v[22:23], v[156:157]
	v_pk_mul_f32 v[18:19], v[18:19], v[196:197]
	v_pk_mul_f32 v[28:29], v[28:29], v[146:147]
	v_pk_mul_f32 v[24:25], v[24:25], v[150:151]
	v_pk_mul_f32 v[20:21], v[20:21], v[154:155]
	v_pk_mul_f32 v[16:17], v[16:17], v[194:195]
	v_pk_mul_f32 v[14:15], v[14:15], v[148:149]
	v_pk_mul_f32 v[10:11], v[10:11], v[152:153]
	v_pk_mul_f32 v[6:7], v[6:7], v[156:157]
	v_pk_mul_f32 v[2:3], v[2:3], v[196:197]
	v_pk_mul_f32 v[12:13], v[12:13], v[146:147]
	v_pk_mul_f32 v[8:9], v[8:9], v[150:151]
	v_pk_mul_f32 v[4:5], v[4:5], v[154:155]
	v_pk_mul_f32 v[0:1], v[0:1], v[194:195]

.Lhs2_top:
	ds_read_b128 v[64:67], v180 offset:32768
	ds_read_b128 v[68:71], v180 offset:40960
	ds_read_b128 v[218:221], v179 offset:32768
	ds_read_b128 v[222:225], v179 offset:40960
	ds_read_b128 v[248:251], v165 offset:32768
	ds_read_b128 v[252:255], v165 offset:40960
	v_exp_f32_e32 v211, v211
	v_exp_f32_e32 v212, v212
	s_waitcnt lgkmcnt(5)
	v_mfma_f32_32x32x16_bf16 v[80:95], v[64:67], v[124:127], 0
	v_exp_f32_e32 v213, v213
	v_exp_f32_e32 v214, v214
	v_exp_f32_e32 v196, v196
	v_exp_f32_e32 v197, v197
	v_exp_f32_e32 v206, v206
	v_exp_f32_e32 v207, v207
	v_exp_f32_e32 v208, v208
	s_waitcnt lgkmcnt(4)
	v_mfma_f32_32x32x16_bf16 v[64:79], v[68:71], v[124:127], 0
	v_exp_f32_e32 v209, v209
	v_exp_f32_e32 v210, v210
	v_exp_f32_e32 v195, v195
	v_exp_f32_e32 v216, v216
	v_exp_f32_e32 v217, v217
	v_exp_f32_e32 v194, v194
	s_waitcnt lgkmcnt(3)
	v_mfma_f32_32x32x16_bf16 v[80:95], v[218:221], v[120:123], v[80:95]
	s_waitcnt lgkmcnt(2)
	v_mfma_f32_32x32x16_bf16 v[64:79], v[222:225], v[120:123], v[64:79]
	ds_read_b128 v[218:221], v163 offset:32768
	ds_read_b128 v[222:225], v163 offset:40960
	s_waitcnt lgkmcnt(3)
	v_mfma_f32_32x32x16_bf16 v[80:95], v[248:251], v[116:119], v[80:95]
	s_waitcnt lgkmcnt(2)
	v_mfma_f32_32x32x16_bf16 v[64:79], v[252:255], v[116:119], v[64:79]
	ds_read_b128 v[248:251], v180 offset:32896
	ds_read_b128 v[252:255], v180 offset:41088
	s_waitcnt lgkmcnt(3)
	v_mfma_f32_32x32x16_bf16 v[80:95], v[218:221], v[112:115], v[80:95]
	s_waitcnt lgkmcnt(2)
	v_mfma_f32_32x32x16_bf16 v[64:79], v[222:225], v[112:115], v[64:79]
	ds_read_b128 v[218:221], v179 offset:32896
	ds_read_b128 v[222:225], v179 offset:41088
	s_waitcnt lgkmcnt(3)
	v_mfma_f32_32x32x16_bf16 v[80:95], v[248:251], v[108:111], v[80:95]
	s_waitcnt lgkmcnt(2)
	v_mfma_f32_32x32x16_bf16 v[64:79], v[252:255], v[108:111], v[64:79]
	ds_read_b128 v[248:251], v165 offset:32896
	ds_read_b128 v[252:255], v165 offset:41088
	s_waitcnt lgkmcnt(3)
	v_mfma_f32_32x32x16_bf16 v[80:95], v[218:221], v[104:107], v[80:95]
	s_waitcnt lgkmcnt(2)
	v_mfma_f32_32x32x16_bf16 v[64:79], v[222:225], v[104:107], v[64:79]
	ds_read_b128 v[218:221], v163 offset:32896
	ds_read_b128 v[222:225], v163 offset:41088
	s_waitcnt lgkmcnt(3)
	v_mfma_f32_32x32x16_bf16 v[80:95], v[248:251], v[100:103], v[80:95]
	s_waitcnt lgkmcnt(2)
	v_mfma_f32_32x32x16_bf16 v[64:79], v[252:255], v[100:103], v[64:79]
	s_waitcnt lgkmcnt(1)
	v_mfma_f32_32x32x16_bf16 v[80:95], v[218:221], v[96:99], v[80:95]
	v_exp_f32_e32 v219, v215
	v_add_f32_e32 v215, 0, v144
	v_add_f32_e32 v215, v159, v215
	v_add_f32_e32 v215, v145, v215
	v_add_f32_e32 v215, v158, v215
	v_add_f32_e32 v215, v146, v215
	v_add_f32_e32 v215, v157, v215
	v_add_f32_e32 v215, v147, v215
	v_add_f32_e32 v215, v156, v215
	v_add_f32_e32 v215, v148, v215
	v_add_f32_e32 v215, v155, v215
	v_add_f32_e32 v215, v149, v215
	v_add_f32_e32 v215, v154, v215
	v_add_f32_e32 v215, v150, v215
	v_add_f32_e32 v215, v153, v215
	v_add_f32_e32 v215, v151, v215
	v_add_f32_e32 v215, v152, v215
	v_add_f32_e32 v215, v211, v215
	v_add_f32_e32 v215, v212, v215
	v_add_f32_e32 v215, v213, v215
	v_add_f32_e32 v215, v214, v215
	v_add_f32_e32 v215, v219, v215
	v_add_f32_e32 v215, v196, v215
	v_add_f32_e32 v215, v197, v215
	v_add_f32_e32 v215, v206, v215
	v_add_f32_e32 v215, v207, v215
	v_add_f32_e32 v215, v208, v215
	s_waitcnt lgkmcnt(0)
	v_mfma_f32_32x32x16_bf16 v[64:79], v[222:225], v[96:99], v[64:79]
	v_add_f32_e32 v215, v209, v215
	v_add_f32_e32 v215, v210, v215
	v_add_f32_e32 v215, v195, v215
	v_add_f32_e32 v215, v216, v215
	v_add_f32_e32 v215, v217, v215
	v_add_f32_e32 v215, v194, v215
	v_mov_b32_e32 v218, v215
	s_nop 0
	v_cvt_pk_bf16_f32 v144, v144, v159
	s_nop 0
	v_cvt_pk_bf16_f32 v145, v145, v158
	s_nop 0
	v_cvt_pk_bf16_f32 v146, v146, v157
	s_nop 0
	v_cvt_pk_bf16_f32 v147, v147, v156
	s_nop 0
	v_cvt_pk_bf16_f32 v148, v148, v155
	s_nop 0
	v_cvt_pk_bf16_f32 v149, v149, v154
	s_nop 0
	v_cvt_pk_bf16_f32 v150, v150, v153
	s_nop 0
	v_cvt_pk_bf16_f32 v151, v151, v152
	s_nop 0
	v_cvt_pk_bf16_f32 v152, v211, v212
	s_nop 0
	v_cvt_pk_bf16_f32 v153, v213, v214
	s_nop 0
	v_cvt_pk_bf16_f32 v154, v219, v196
	s_nop 0
	v_cvt_pk_bf16_f32 v155, v197, v206
	s_nop 0
	v_cvt_pk_bf16_f32 v156, v207, v208
	s_nop 0
	v_cvt_pk_bf16_f32 v157, v209, v210
	s_nop 0
	v_cvt_pk_bf16_f32 v158, v195, v216
	s_nop 0
	v_cvt_pk_bf16_f32 v159, v217, v194
	s_nop 1
	v_permlane32_swap_b32_e32 v215, v218
	v_permlane32_swap_b32_e32 v144, v146
	v_permlane32_swap_b32_e32 v145, v147
	v_permlane32_swap_b32_e32 v148, v150
	v_permlane32_swap_b32_e32 v149, v151
	v_permlane32_swap_b32_e32 v152, v154
	v_permlane32_swap_b32_e32 v153, v155
	v_permlane32_swap_b32_e32 v156, v158
	v_permlane32_swap_b32_e32 v157, v159
	s_add_i32 s0, s25, 1
	s_cmp_lt_u32 s0, s23
	s_cselect_b64 s[2:3], -1, 0
	s_cmp_ge_u32 s0, s23
	s_cbranch_scc1 .LBB0_201
	v_add_u32_e32 v128, 0x41, v192
	v_add_u32_e32 v130, 0x61, v192
	v_ashrrev_i32_e32 v129, 31, v128
	v_ashrrev_i32_e32 v131, 31, v130
	v_lshlrev_b64 v[136:137], 8, v[128:129]
	v_lshlrev_b64 v[138:139], 8, v[130:131]
	v_lshl_add_u64 v[128:129], v[166:167], 0, v[136:137]
	v_lshl_add_u64 v[132:133], v[166:167], 0, v[138:139]
	v_lshl_add_u64 v[136:137], v[168:169], 0, v[136:137]
	v_lshl_add_u64 v[140:141], v[168:169], 0, v[138:139]
	global_load_dwordx4 v[128:131], v[128:129], off
	s_nop 0
	global_load_dwordx4 v[132:135], v[132:133], off
	s_nop 0
	global_load_dwordx4 v[136:139], v[136:137], off
	s_nop 0
	global_load_dwordx4 v[140:143], v[140:141], off
.LBB0_201:
	ds_read_b64_tr_b16 v[194:195], v173 offset:0x4000
	ds_read_b64_tr_b16 v[196:197], v173 offset:0x4800
	ds_read_b64_tr_b16 v[206:207], v173 offset:0x5000
	ds_read_b64_tr_b16 v[208:209], v173 offset:0x5800
	ds_read_b64_tr_b16 v[210:211], v173 offset:0x6000
	ds_read_b64_tr_b16 v[212:213], v173 offset:0x6800
	ds_read_b64_tr_b16 v[220:221], v173 offset:0x7000
	ds_read_b64_tr_b16 v[222:223], v173 offset:0x7800
	s_waitcnt lgkmcnt(0)
	s_add_i32 s0, s26, 64
	s_add_i32 s27, s26, 1
	v_mfma_f32_32x32x16_bf16 v[48:63], v[144:147], v[194:197], v[48:63]
	ds_read_b64_tr_b16 v[194:195], v173 offset:0x4200
	ds_read_b64_tr_b16 v[196:197], v173 offset:0x4a00
	v_mfma_f32_32x32x16_bf16 v[48:63], v[148:151], v[206:209], v[48:63]
	ds_read_b64_tr_b16 v[206:207], v173 offset:0x5200
	ds_read_b64_tr_b16 v[208:209], v173 offset:0x5a00
	v_mfma_f32_32x32x16_bf16 v[48:63], v[152:155], v[210:213], v[48:63]
	ds_read_b64_tr_b16 v[210:211], v173 offset:0x6200
	ds_read_b64_tr_b16 v[212:213], v173 offset:0x6a00
	v_mfma_f32_32x32x16_bf16 v[48:63], v[156:159], v[220:223], v[48:63]
	ds_read_b64_tr_b16 v[220:221], v173 offset:0x7200
	ds_read_b64_tr_b16 v[222:223], v173 offset:0x7a00
	s_waitcnt lgkmcnt(0)
	v_mfma_f32_32x32x16_bf16 v[32:47], v[144:147], v[194:197], v[32:47]
	ds_read_b64_tr_b16 v[194:195], v173 offset:0x4400
	ds_read_b64_tr_b16 v[196:197], v173 offset:0x4c00
	v_mfma_f32_32x32x16_bf16 v[32:47], v[148:151], v[206:209], v[32:47]
	ds_read_b64_tr_b16 v[206:207], v173 offset:0x5400
	ds_read_b64_tr_b16 v[208:209], v173 offset:0x5c00
	v_mfma_f32_32x32x16_bf16 v[32:47], v[152:155], v[210:213], v[32:47]
	ds_read_b64_tr_b16 v[210:211], v173 offset:0x6400
	ds_read_b64_tr_b16 v[212:213], v173 offset:0x6c00
	v_mfma_f32_32x32x16_bf16 v[32:47], v[156:159], v[220:223], v[32:47]
	ds_read_b64_tr_b16 v[220:221], v173 offset:0x7400
	ds_read_b64_tr_b16 v[222:223], v173 offset:0x7c00
	s_waitcnt lgkmcnt(0)
	v_mfma_f32_32x32x16_bf16 v[16:31], v[144:147], v[194:197], v[16:31]
	ds_read_b64_tr_b16 v[194:195], v173 offset:0x4600
	ds_read_b64_tr_b16 v[196:197], v173 offset:0x4e00
	v_mfma_f32_32x32x16_bf16 v[16:31], v[148:151], v[206:209], v[16:31]
	ds_read_b64_tr_b16 v[206:207], v173 offset:0x5600
	ds_read_b64_tr_b16 v[208:209], v173 offset:0x5e00
	v_mfma_f32_32x32x16_bf16 v[16:31], v[152:155], v[210:213], v[16:31]
	ds_read_b64_tr_b16 v[210:211], v173 offset:0x6600
	ds_read_b64_tr_b16 v[212:213], v173 offset:0x6e00
	v_mfma_f32_32x32x16_bf16 v[16:31], v[156:159], v[220:223], v[16:31]
	ds_read_b64_tr_b16 v[220:221], v173 offset:0x7600
	ds_read_b64_tr_b16 v[222:223], v173 offset:0x7e00
	s_waitcnt lgkmcnt(0)
	v_mfma_f32_32x32x16_bf16 v[0:15], v[144:147], v[194:197], v[0:15]
	s_cmp_le_i32 s0, s19
	s_cselect_b64 s[0:1], -1, 0
	s_cmp_gt_i32 s27, s24
	s_cselect_b64 s[28:29], -1, 0
	s_and_b64 s[0:1], s[0:1], s[28:29]
	s_and_b64 vcc, exec, s[0:1]
	v_mfma_f32_32x32x16_bf16 v[0:15], v[148:151], v[206:209], v[0:15]
	v_mfma_f32_32x32x16_bf16 v[0:15], v[152:155], v[210:213], v[0:15]
	v_mfma_f32_32x32x16_bf16 v[0:15], v[156:159], v[220:223], v[0:15]
	s_cmp_eq_u64 s[2:3], 0
	s_cbranch_scc1 .Lhs2_no_kstage
	s_waitcnt vmcnt(0)
	ds_write_b128 v176, v[136:139] offset:49152
	ds_write_b128 v176, v[140:143] offset:57344
.Lhs2_no_kstage:
	s_cbranch_vccnz .LBB0_203
	v_add_u32_e32 v144, 0x203b, v188
	v_cmp_gt_u32_e32 vcc, s73, v144
	v_add_u32_e32 v144, 27, v188
	s_nop 0
	v_cndmask_b32_e32 v80, v202, v80, vcc
	v_cmp_lt_u32_e32 vcc, s95, v144
	v_add_u32_e32 v144, 58, v188
	s_nop 0
	v_cndmask_b32_e32 v64, v202, v64, vcc
	v_cmp_lt_u32_e32 vcc, s95, v144
	v_add_u32_e32 v144, 26, v188
	s_nop 0
	v_cndmask_b32_e32 v81, v202, v81, vcc
	v_cmp_lt_u32_e32 vcc, s95, v144
	v_add_u32_e32 v144, 57, v188
	s_nop 0
	v_cndmask_b32_e32 v65, v202, v65, vcc
	v_cmp_lt_u32_e32 vcc, s95, v144
	v_add_u32_e32 v144, 25, v188
	s_nop 0
	v_cndmask_b32_e32 v82, v202, v82, vcc
	v_cmp_lt_u32_e32 vcc, s95, v144
	v_add_u32_e32 v144, 56, v188
	s_nop 0
	v_cndmask_b32_e32 v66, v202, v66, vcc
	v_cmp_lt_u32_e32 vcc, s95, v144
	v_add_u32_e32 v144, 24, v188
	s_nop 0
	v_cndmask_b32_e32 v83, v202, v83, vcc
	v_cmp_lt_u32_e32 vcc, s95, v144
	v_add_u32_e32 v144, 51, v188
	s_nop 0
	v_cndmask_b32_e32 v67, v202, v67, vcc
	v_cmp_lt_u32_e32 vcc, s95, v144
	v_add_u32_e32 v144, 19, v188
	s_nop 0
	v_cndmask_b32_e32 v84, v202, v84, vcc
	v_cmp_lt_u32_e32 vcc, s95, v144
	v_add_u32_e32 v144, 50, v188
	s_nop 0
	v_cndmask_b32_e32 v68, v202, v68, vcc
	v_cmp_lt_u32_e32 vcc, s95, v144
	v_add_u32_e32 v144, 18, v188
	s_nop 0
	v_cndmask_b32_e32 v85, v202, v85, vcc
	v_cmp_lt_u32_e32 vcc, s95, v144
	v_add_u32_e32 v144, 49, v188
	s_nop 0
	v_cndmask_b32_e32 v69, v202, v69, vcc
	v_cmp_lt_u32_e32 vcc, s95, v144
	v_add_u32_e32 v144, 17, v188
	s_nop 0
	v_cndmask_b32_e32 v86, v202, v86, vcc
	v_cmp_lt_u32_e32 vcc, s95, v144
	v_add_u32_e32 v144, 48, v188
	s_nop 0
	v_cndmask_b32_e32 v70, v202, v70, vcc
	v_cmp_lt_u32_e32 vcc, s95, v144
	v_add_u32_e32 v144, 16, v188
	s_nop 0
	v_cndmask_b32_e32 v87, v202, v87, vcc
	v_cmp_lt_u32_e32 vcc, s95, v144
	v_add_u32_e32 v144, 43, v188
	s_nop 0
	v_cndmask_b32_e32 v71, v202, v71, vcc
	v_cmp_lt_u32_e32 vcc, s95, v144
	v_add_u32_e32 v144, 11, v188
	s_nop 0
	v_cndmask_b32_e32 v88, v202, v88, vcc
	v_cmp_lt_u32_e32 vcc, s95, v144
	v_add_u32_e32 v144, 42, v188
	s_nop 0
	v_cndmask_b32_e32 v72, v202, v72, vcc
	v_cmp_lt_u32_e32 vcc, s95, v144
	v_add_u32_e32 v144, 10, v188
	s_nop 0
	v_cndmask_b32_e32 v89, v202, v89, vcc
	v_cmp_lt_u32_e32 vcc, s95, v144
	v_add_u32_e32 v144, 41, v188
	s_nop 0
	v_cndmask_b32_e32 v73, v202, v73, vcc
	v_cmp_lt_u32_e32 vcc, s95, v144
	v_add_u32_e32 v144, 9, v188
	s_nop 0
	v_cndmask_b32_e32 v90, v202, v90, vcc
	v_cmp_lt_u32_e32 vcc, s95, v144
	v_add_u32_e32 v144, 40, v188
	s_nop 0
	v_cndmask_b32_e32 v74, v202, v74, vcc
	v_cmp_lt_u32_e32 vcc, s95, v144
	v_add_u32_e32 v144, 8, v188
	s_nop 0
	v_cndmask_b32_e32 v91, v202, v91, vcc
	v_cmp_lt_u32_e32 vcc, s95, v144
	v_add_u32_e32 v144, 35, v188
	s_nop 0
	v_cndmask_b32_e32 v75, v202, v75, vcc
	v_cmp_lt_u32_e32 vcc, s95, v144
	v_add_u32_e32 v144, 3, v188
	s_nop 0
	v_cndmask_b32_e32 v92, v202, v92, vcc
	v_cmp_lt_u32_e32 vcc, s95, v144
	v_add_u32_e32 v144, 34, v188
	s_nop 0
	v_cndmask_b32_e32 v76, v202, v76, vcc
	v_cmp_lt_u32_e32 vcc, s95, v144
	v_add_u32_e32 v144, 2, v188
	s_nop 0
	v_cndmask_b32_e32 v93, v202, v93, vcc
	v_cmp_lt_u32_e32 vcc, s95, v144
	v_add_u32_e32 v144, 33, v188
	s_nop 0
	v_cndmask_b32_e32 v77, v202, v77, vcc
	v_cmp_lt_u32_e32 vcc, s95, v144
	v_add_u32_e32 v144, 1, v188
	s_nop 0
	v_cndmask_b32_e32 v94, v202, v94, vcc
	v_cmp_lt_u32_e32 vcc, s95, v144
	v_add_u32_e32 v144, 32, v188
	s_nop 0
	v_cndmask_b32_e32 v78, v202, v78, vcc
	v_cmp_lt_u32_e32 vcc, s95, v144
	s_nop 1
	v_cndmask_b32_e32 v95, v202, v95, vcc
	v_cmp_lt_u32_e32 vcc, s95, v188
	s_nop 1
	v_cndmask_b32_e32 v79, v202, v79, vcc
.LBB0_203:
	v_max_f32_e32 v144, v81, v81
	v_max_f32_e32 v145, v80, v80
	v_max_f32_e32 v144, v145, v144
	v_max3_f32 v144, v144, v82, v83
	v_max3_f32 v144, v144, v84, v85
	v_max3_f32 v144, v144, v86, v87
	v_max3_f32 v144, v144, v88, v89
	v_max3_f32 v144, v144, v90, v91
	v_max3_f32 v144, v144, v92, v93
	v_max3_f32 v144, v144, v94, v95
	v_max3_f32 v144, v144, v64, v65
	v_max3_f32 v144, v144, v66, v67
	v_max3_f32 v144, v144, v68, v69
	v_max3_f32 v144, v144, v70, v71
	v_max3_f32 v144, v144, v72, v73
	v_max3_f32 v144, v144, v74, v75
	v_max3_f32 v144, v144, v76, v77
	v_max3_f32 v144, v144, v78, v79
	v_mov_b32_e32 v145, v144
	s_nop 1
	v_permlane32_swap_b32_e32 v144, v145
	v_max_f32_e32 v145, v145, v145
	v_max_f32_e32 v144, v144, v144
	v_max_f32_e32 v144, v144, v145
	v_sub_f32_e32 v145, v144, v186
	v_mul_f32_e32 v145, 0x3db504f3, v145
	v_cmp_ge_f32_e32 vcc, s87, v145
	s_cmp_eq_u64 vcc, exec
	s_cselect_b64 s[0:1], -1, 0
	s_andn2_b64 vcc, exec, s[2:3]
	v_readfirstlane_b32 s27, v187
	s_nop 3
	s_cmpk_lt_u32 s27, 0x100
	s_cbranch_scc1 .Lg1b_hs2
	s_waitcnt lgkmcnt(0)
	s_barrier
	s_cbranch_vccnz .LBB0_205
	s_waitcnt vmcnt(0)
	s_waitcnt vmcnt(3)
	ds_write_b128 v181, v[128:131] offset:16384
	s_waitcnt vmcnt(2)
	ds_write_b128 v182, v[132:135] offset:16384

.LBB0_209:
	v_cndmask_b32_e64 v186, v128, v186, s[0:1]
	v_mul_f32_e32 v128, 0xbe0293ee, v186
	v_mov_b32_e32 v129, v128
	v_fmamk_f32 v80, v80, 0x3e0293ee, v128
	v_fmamk_f32 v81, v81, 0x3e0293ee, v128
	v_fmamk_f32 v82, v82, 0x3e0293ee, v128
	v_fmamk_f32 v83, v83, 0x3e0293ee, v128
	v_fmamk_f32 v84, v84, 0x3e0293ee, v128
	v_fmamk_f32 v85, v85, 0x3e0293ee, v128
	v_fmamk_f32 v86, v86, 0x3e0293ee, v128
	v_fmamk_f32 v87, v87, 0x3e0293ee, v128
	v_fmamk_f32 v88, v88, 0x3e0293ee, v128
	v_fmamk_f32 v89, v89, 0x3e0293ee, v128
	v_fmamk_f32 v90, v90, 0x3e0293ee, v128
	v_fmamk_f32 v91, v91, 0x3e0293ee, v128
	v_fmamk_f32 v92, v92, 0x3e0293ee, v128
	v_fmamk_f32 v93, v93, 0x3e0293ee, v128
	v_fmamk_f32 v94, v94, 0x3e0293ee, v128
	v_fmac_f32_e32 v129, 0x3e0293ee, v95
	v_exp_f32_e32 v216, v80
	v_exp_f32_e32 v219, v81
	v_exp_f32_e32 v213, v82
	v_exp_f32_e32 v217, v83
	v_exp_f32_e32 v212, v84
	v_exp_f32_e32 v214, v85
	v_exp_f32_e32 v210, v86
	v_exp_f32_e32 v211, v87
	v_exp_f32_e32 v207, v88
	v_exp_f32_e32 v209, v89
	v_exp_f32_e32 v206, v90
	v_exp_f32_e32 v208, v91
	v_exp_f32_e32 v195, v92
	v_exp_f32_e32 v197, v93
	v_exp_f32_e32 v194, v94
	v_exp_f32_e32 v196, v129
	v_pk_fma_f32 v[156:157], v[64:65], s[90:91], v[128:129] op_sel_hi:[1,0,0]
	v_add_f32_e32 v64, v190, v191
	v_fmac_f32_e32 v64, v183, v177
	v_add_f32_e32 v177, v215, v218
	s_addk_i32 s26, 0x80
	s_add_i32 s25, s25, 2
	v_pk_fma_f32 v[154:155], v[66:67], s[90:91], v[128:129] op_sel_hi:[1,0,0]
	v_pk_fma_f32 v[150:151], v[68:69], s[90:91], v[128:129] op_sel_hi:[1,0,0]
	v_pk_fma_f32 v[148:149], v[70:71], s[90:91], v[128:129] op_sel_hi:[1,0,0]
	v_pk_fma_f32 v[144:145], v[72:73], s[90:91], v[128:129] op_sel_hi:[1,0,0]
	v_pk_fma_f32 v[158:159], v[74:75], s[90:91], v[128:129] op_sel_hi:[1,0,0]
	v_pk_fma_f32 v[152:153], v[76:77], s[90:91], v[128:129] op_sel_hi:[1,0,0]
	v_pk_fma_f32 v[146:147], v[78:79], s[90:91], v[128:129] op_sel_hi:[1,0,0]
	s_mov_b64 s[28:29], 0x14000080
	v_fmac_f32_e32 v177, v64, v193
	s_cmp_lt_u32 s25, s23
	v_add_u32_e32 v188, 0xffffff80, v188
	s_cbranch_scc0 .LBB0_211
	v_mov_b32_e32 v183, v192
	s_branch .LBB0_193
.Lg1b_hs1:
	v_cndmask_b32_e64 v193, v145, 1.0, s[0:1]
	v_cmp_gt_f32_e32 vcc, 1.0, v193
	s_cbranch_vccz .Lg1b_199
	s_and_saveexec_b64 s[2:3], s[4:5]
	ds_write_b32 v175, v193 offset:128
	s_or_b64 exec, exec, s[2:3]
	s_waitcnt lgkmcnt(0)
	ds_read_b128 v[146:149], v174 offset:224
	ds_read_b128 v[150:153], v174 offset:192
	ds_read_b128 v[154:157], v174 offset:160
	ds_read_b128 v[194:197], v174 offset:128
	s_waitcnt lgkmcnt(3)
	v_pk_mul_f32 v[62:63], v[62:63], v[148:149]
	s_waitcnt lgkmcnt(2)
	v_pk_mul_f32 v[58:59], v[58:59], v[152:153]
	s_waitcnt lgkmcnt(1)
	v_pk_mul_f32 v[54:55], v[54:55], v[156:157]
	s_waitcnt lgkmcnt(0)
	v_pk_mul_f32 v[50:51], v[50:51], v[196:197]
	v_pk_mul_f32 v[60:61], v[60:61], v[146:147]
	v_pk_mul_f32 v[56:57], v[56:57], v[150:151]
	v_pk_mul_f32 v[52:53], v[52:53], v[154:155]
	v_pk_mul_f32 v[48:49], v[48:49], v[194:195]
	v_pk_mul_f32 v[46:47], v[46:47], v[148:149]
	v_pk_mul_f32 v[42:43], v[42:43], v[152:153]
	v_pk_mul_f32 v[38:39], v[38:39], v[156:157]
	v_pk_mul_f32 v[34:35], v[34:35], v[196:197]
	v_pk_mul_f32 v[44:45], v[44:45], v[146:147]
	v_pk_mul_f32 v[40:41], v[40:41], v[150:151]
	v_pk_mul_f32 v[36:37], v[36:37], v[154:155]
	v_pk_mul_f32 v[32:33], v[32:33], v[194:195]
	v_pk_mul_f32 v[30:31], v[30:31], v[148:149]
	v_pk_mul_f32 v[26:27], v[26:27], v[152:153]
	v_pk_mul_f32 v[22:23], v[22:23], v[156:157]
	v_pk_mul_f32 v[18:19], v[18:19], v[196:197]
	v_pk_mul_f32 v[28:29], v[28:29], v[146:147]
	v_pk_mul_f32 v[24:25], v[24:25], v[150:151]
	v_pk_mul_f32 v[20:21], v[20:21], v[154:155]
	v_pk_mul_f32 v[16:17], v[16:17], v[194:195]
	v_pk_mul_f32 v[14:15], v[14:15], v[148:149]
	v_pk_mul_f32 v[10:11], v[10:11], v[152:153]
	v_pk_mul_f32 v[6:7], v[6:7], v[156:157]
	v_pk_mul_f32 v[2:3], v[2:3], v[196:197]
	v_pk_mul_f32 v[12:13], v[12:13], v[146:147]
	v_pk_mul_f32 v[8:9], v[8:9], v[150:151]
	v_pk_mul_f32 v[4:5], v[4:5], v[154:155]
	v_pk_mul_f32 v[0:1], v[0:1], v[194:195]
.Lg1b_199:
	v_cndmask_b32_e64 v186, v144, v186, s[0:1]
	v_mul_f32_e32 v194, 0xbe0293ee, v186
	v_fmamk_f32 v80, v80, 0x3e0293ee, v194
	v_fmamk_f32 v81, v81, 0x3e0293ee, v194
	v_fmamk_f32 v82, v82, 0x3e0293ee, v194
	v_fmamk_f32 v83, v83, 0x3e0293ee, v194
	v_fmamk_f32 v84, v84, 0x3e0293ee, v194
	v_fmamk_f32 v85, v85, 0x3e0293ee, v194
	v_fmamk_f32 v86, v86, 0x3e0293ee, v194
	v_fmamk_f32 v87, v87, 0x3e0293ee, v194
	v_fmamk_f32 v88, v88, 0x3e0293ee, v194
	v_fmamk_f32 v89, v89, 0x3e0293ee, v194
	v_fmamk_f32 v90, v90, 0x3e0293ee, v194
	v_fmamk_f32 v91, v91, 0x3e0293ee, v194
	v_fmamk_f32 v92, v92, 0x3e0293ee, v194
	v_fmamk_f32 v93, v93, 0x3e0293ee, v194
	v_fmamk_f32 v94, v94, 0x3e0293ee, v194
	v_fmamk_f32 v95, v95, 0x3e0293ee, v194
	v_exp_f32_e32 v144, v80
	v_exp_f32_e32 v159, v81
	v_exp_f32_e32 v145, v82
	v_exp_f32_e32 v158, v83
	v_exp_f32_e32 v146, v84
	v_exp_f32_e32 v157, v85
	v_exp_f32_e32 v147, v86
	v_exp_f32_e32 v156, v87
	v_exp_f32_e32 v148, v88
	v_exp_f32_e32 v155, v89
	v_exp_f32_e32 v149, v90
	v_exp_f32_e32 v154, v91
	v_exp_f32_e32 v150, v92
	v_exp_f32_e32 v153, v93
	v_exp_f32_e32 v151, v94
	v_exp_f32_e32 v152, v95
	v_fmamk_f32 v215, v68, 0x3e0293ee, v194
	v_fmamk_f32 v211, v64, 0x3e0293ee, v194
	v_fmamk_f32 v212, v65, 0x3e0293ee, v194
	v_fmamk_f32 v213, v66, 0x3e0293ee, v194
	v_fmamk_f32 v214, v67, 0x3e0293ee, v194
	v_fmamk_f32 v196, v69, 0x3e0293ee, v194
	v_fmamk_f32 v197, v70, 0x3e0293ee, v194
	v_fmamk_f32 v206, v71, 0x3e0293ee, v194
	v_fmamk_f32 v207, v72, 0x3e0293ee, v194
	v_fmamk_f32 v208, v73, 0x3e0293ee, v194
	v_fmamk_f32 v209, v74, 0x3e0293ee, v194
	v_fmamk_f32 v210, v75, 0x3e0293ee, v194
	v_fmamk_f32 v195, v76, 0x3e0293ee, v194
	v_fmamk_f32 v216, v77, 0x3e0293ee, v194
	v_fmamk_f32 v217, v78, 0x3e0293ee, v194
	v_fmac_f32_e32 v194, 0x3e0293ee, v79
	s_waitcnt lgkmcnt(0)
	s_barrier
	ds_write_b128 v181, v[128:131]
	ds_write_b128 v182, v[132:135]
	s_branch .Lhs2_top
.Lg1b_hs2:
	v_max_f32_e32 v136, v186, v186
	v_max_f32_e32 v136, v136, v144
	v_sub_f32_e32 v137, v186, v136
	v_mul_f32_e32 v137, 0x3e0293ee, v137
	v_exp_f32_e32 v137, v137
	s_nop 0
	v_cndmask_b32_e64 v192, v137, 1.0, s[0:1]
	v_cmp_gt_f32_e32 vcc, 1.0, v192
	s_cbranch_vccz .Lg1b_209
	s_and_saveexec_b64 s[28:29], s[4:5]
	ds_write_b32 v175, v192 offset:128
	s_or_b64 exec, exec, s[28:29]
	s_waitcnt lgkmcnt(0)
	ds_read_b128 v[146:149], v174 offset:224
	ds_read_b128 v[150:153], v174 offset:192
	ds_read_b128 v[194:197], v174 offset:160
	ds_read_b128 v[206:209], v174 offset:128
	s_waitcnt lgkmcnt(3)
	v_pk_mul_f32 v[62:63], v[62:63], v[148:149]
	s_waitcnt lgkmcnt(2)
	v_pk_mul_f32 v[58:59], v[58:59], v[152:153]
	s_waitcnt lgkmcnt(1)
	v_pk_mul_f32 v[54:55], v[54:55], v[196:197]
	s_waitcnt lgkmcnt(0)
	v_pk_mul_f32 v[50:51], v[50:51], v[208:209]
	v_pk_mul_f32 v[60:61], v[60:61], v[146:147]
	v_pk_mul_f32 v[56:57], v[56:57], v[150:151]
	v_pk_mul_f32 v[52:53], v[52:53], v[194:195]
	v_pk_mul_f32 v[48:49], v[48:49], v[206:207]
	v_pk_mul_f32 v[46:47], v[46:47], v[148:149]
	v_pk_mul_f32 v[42:43], v[42:43], v[152:153]
	v_pk_mul_f32 v[38:39], v[38:39], v[196:197]
	v_pk_mul_f32 v[34:35], v[34:35], v[208:209]
	v_pk_mul_f32 v[44:45], v[44:45], v[146:147]
	v_pk_mul_f32 v[40:41], v[40:41], v[150:151]
	v_pk_mul_f32 v[36:37], v[36:37], v[194:195]
	v_pk_mul_f32 v[32:33], v[32:33], v[206:207]
	v_pk_mul_f32 v[30:31], v[30:31], v[148:149]
	v_pk_mul_f32 v[26:27], v[26:27], v[152:153]
	v_pk_mul_f32 v[22:23], v[22:23], v[196:197]
	v_pk_mul_f32 v[18:19], v[18:19], v[208:209]
	v_pk_mul_f32 v[28:29], v[28:29], v[146:147]
	v_pk_mul_f32 v[24:25], v[24:25], v[150:151]
	v_pk_mul_f32 v[20:21], v[20:21], v[194:195]
	v_pk_mul_f32 v[16:17], v[16:17], v[206:207]
	v_pk_mul_f32 v[14:15], v[14:15], v[148:149]
	v_pk_mul_f32 v[10:11], v[10:11], v[152:153]
	v_pk_mul_f32 v[6:7], v[6:7], v[196:197]
	v_pk_mul_f32 v[2:3], v[2:3], v[208:209]
	v_pk_mul_f32 v[12:13], v[12:13], v[146:147]
	v_pk_mul_f32 v[8:9], v[8:9], v[150:151]
	v_pk_mul_f32 v[4:5], v[4:5], v[194:195]
	v_pk_mul_f32 v[0:1], v[0:1], v[206:207]
.Lg1b_209:
	v_cndmask_b32_e64 v186, v136, v186, s[0:1]
	v_mul_f32_e32 v136, 0xbe0293ee, v186
	v_mov_b32_e32 v137, v136
	v_fmamk_f32 v80, v80, 0x3e0293ee, v136
	v_fmamk_f32 v81, v81, 0x3e0293ee, v136
	v_fmamk_f32 v82, v82, 0x3e0293ee, v136
	v_fmamk_f32 v83, v83, 0x3e0293ee, v136
	v_fmamk_f32 v84, v84, 0x3e0293ee, v136
	v_fmamk_f32 v85, v85, 0x3e0293ee, v136
	v_fmamk_f32 v86, v86, 0x3e0293ee, v136
	v_fmamk_f32 v87, v87, 0x3e0293ee, v136
	v_fmamk_f32 v88, v88, 0x3e0293ee, v136
	v_fmamk_f32 v89, v89, 0x3e0293ee, v136
	v_fmamk_f32 v90, v90, 0x3e0293ee, v136
	v_fmamk_f32 v91, v91, 0x3e0293ee, v136
	v_fmamk_f32 v92, v92, 0x3e0293ee, v136
	v_fmamk_f32 v93, v93, 0x3e0293ee, v136
	v_fmamk_f32 v94, v94, 0x3e0293ee, v136
	v_fmac_f32_e32 v137, 0x3e0293ee, v95
	v_exp_f32_e32 v216, v80
	v_exp_f32_e32 v219, v81
	v_exp_f32_e32 v213, v82
	v_exp_f32_e32 v217, v83
	v_exp_f32_e32 v212, v84
	v_exp_f32_e32 v214, v85
	v_exp_f32_e32 v210, v86
	v_exp_f32_e32 v211, v87
	v_exp_f32_e32 v207, v88
	v_exp_f32_e32 v209, v89
	v_exp_f32_e32 v206, v90
	v_exp_f32_e32 v208, v91
	v_exp_f32_e32 v195, v92
	v_exp_f32_e32 v197, v93
	v_exp_f32_e32 v194, v94
	v_exp_f32_e32 v196, v137
	v_pk_fma_f32 v[156:157], v[64:65], s[90:91], v[136:137] op_sel_hi:[1,0,0]
	v_add_f32_e32 v64, v190, v191
	v_fmac_f32_e32 v64, v183, v177
	v_add_f32_e32 v177, v215, v218
	s_addk_i32 s26, 0x80
	s_add_i32 s25, s25, 2
	v_pk_fma_f32 v[154:155], v[66:67], s[90:91], v[136:137] op_sel_hi:[1,0,0]
	v_pk_fma_f32 v[150:151], v[68:69], s[90:91], v[136:137] op_sel_hi:[1,0,0]
	v_pk_fma_f32 v[148:149], v[70:71], s[90:91], v[136:137] op_sel_hi:[1,0,0]
	v_pk_fma_f32 v[144:145], v[72:73], s[90:91], v[136:137] op_sel_hi:[1,0,0]
	v_pk_fma_f32 v[158:159], v[74:75], s[90:91], v[136:137] op_sel_hi:[1,0,0]
	v_pk_fma_f32 v[152:153], v[76:77], s[90:91], v[136:137] op_sel_hi:[1,0,0]
	v_pk_fma_f32 v[146:147], v[78:79], s[90:91], v[136:137] op_sel_hi:[1,0,0]
	s_mov_b64 s[28:29], 0x14000080
	v_fmac_f32_e32 v177, v64, v193
	v_add_u32_e32 v188, 0xffffff80, v188
	s_waitcnt lgkmcnt(0)
	s_barrier
	s_andn2_b64 vcc, exec, s[2:3]
	s_cbranch_vccnz .Lg1b_novw
	ds_write_b128 v181, v[128:131] offset:16384
	ds_write_b128 v182, v[132:135] offset:16384
.Lg1b_novw:
	s_cmp_lt_u32 s25, s23
	s_cbranch_scc0 .LBB0_211
	v_mov_b32_e32 v183, v192
	s_branch .LBB0_193
